# baseline (speedup 1.0000x reference)
; #define HG_ISSUE(c) do { const int p_ = (c) * 32 + lt; const int tok_ = tokbase + (dir ? 511 - p_ : p_); const u16* rp_ = PROJ + (size_t)tok_ * INP + h * 128 + lc; \
;     rq = ld8(rp_ + C_HQ); rf = ld8(rp_ + fcol); rv = ld8(rp_ + C_HI); } while (0)
; #define HG_ISSUE(c) do { const int p_ = (c) * 64 + lt; const int tok_ = tokbase + (dir ? 511 - p_ : p_); const u16* rp_ = PROJ + (size_t)tok_ * INP + h * 128 + lc; \
;     if (MODE == 1) { rq0 = ld8(rp_ + C_HQ); rq1 = ld8(rp_ + C_HQ + 8); } rf0 = ld8(rp_ + fcol); rf1 = ld8(rp_ + fcol + 8); rv0 = ld8(rp_ + C_HI); rv1 = ld8(rp_ + C_HI + 8); } while (0)
; template <int MODE>
; DI void hgrn_item2(const u16* PROJ, int tokbase, int dir, int h, int layer, const float* hgrn_lb, float* Sg, float* Pg,
;                    u16* OH, const float* norm_g, char* lds) {
;     ...
;     if (c + 1 < 8) HG_ISSUE(c + 1);
;     ...
;     uint2 pf_t[4], pf_g[4];
;     if (MODE == 1 && dir == 1) {
;       const int t_ = (wid >> 2) * 32 + r32, pp_ = c * 64 + t_; const int tok_ = tokbase + 511 - pp_;
;       const int cv_ = h * 128 + (wid & 3) * 32 + 4 * hi;
; #pragma unroll
;       for (int q4 = 0; q4 < 4; ++q4) { pf_t[q4] = *reinterpret_cast<const uint2*>(OH + (size_t)tok_ * 1024 + cv_ + 8 * q4);
;         pf_g[q4] = *reinterpret_cast<const uint2*>(PROJ + (size_t)tok_ * INP + C_HG + cv_ + 8 * q4); }
;     }
.LBB0_69:
	s_andn2_b64 vcc, exec, s[86:87]
	s_cbranch_vccnz .Lhg3_nopf
	v_add_u32_e32 v0, s90, v140
	v_ashrrev_i32_e32 v1, 31, v0
	v_mov_b64_e32 v[4:5], s[8:9]
	v_lshlrev_b64 v[2:3], 11, v[0:1]
	v_mad_i64_i32 v[0:1], s[6:7], v0, s33, v[4:5]
	v_lshl_add_u64 v[0:1], v[90:91], 1, v[0:1]
	s_mov_b64 s[6:7], 0x2000
	v_lshl_add_u64 v[2:3], v[92:93], 0, v[2:3]
	v_lshl_add_u64 v[4:5], v[0:1], 0, s[6:7]
	v_add_co_u32_e32 v0, vcc, 0x2000, v0
	s_nop 1
	v_addc_co_u32_e32 v1, vcc, 0, v1, vcc
	global_load_dwordx2 v[100:101], v[2:3], off
	global_load_dwordx2 v[102:103], v[2:3], off offset:16
	global_load_dwordx2 v[104:105], v[2:3], off offset:32
	global_load_dwordx2 v[106:107], v[2:3], off offset:48
	global_load_dwordx2 v[114:115], v[0:1], off
	global_load_dwordx2 v[112:113], v[4:5], off offset:16
	global_load_dwordx2 v[110:111], v[4:5], off offset:32
	global_load_dwordx2 v[108:109], v[4:5], off offset:48

; template <int MODE>
; DI void hgrn_item2(const u16* PROJ, int tokbase, int dir, int h, int layer, const float* hgrn_lb, float* Sg, float* Pg,
;                    u16* OH, const float* norm_g, char* lds) {
;     ...
;     uint2 pf_t[4], pf_g[4];
;     if (MODE == 1 && dir == 1) {
;       const int t_ = (wid >> 2) * 32 + r32, pp_ = c * 64 + t_; const int tok_ = tokbase + 511 - pp_;
;       const int cv_ = h * 128 + (wid & 3) * 32 + 4 * hi;
; #pragma unroll
;       for (int q4 = 0; q4 < 4; ++q4) { pf_t[q4] = *reinterpret_cast<const uint2*>(OH + (size_t)tok_ * 1024 + cv_ + 8 * q4);
;         pf_g[q4] = *reinterpret_cast<const uint2*>(PROJ + (size_t)tok_ * INP + C_HG + cv_ + 8 * q4); }
;     }
;     if (MODE == 1) {
;       if (wid < 3) {
.LBB0_81:
	s_and_saveexec_b64 s[6:7], s[44:45]
	s_xor_b64 vcc, exec, s[6:7]
	s_cbranch_execz .LBB0_73
